# k-loop headers aligned to 64 bytes (.p2align 6 in front of the 13 loop labels), otherwise v58
# speedup vs baseline: 1.0029x; 1.0029x over previous
; template <class Epi, class Sched, bool ALIGN_EPI = false, bool SP2 = false>
; __device__ __forceinline__ void gemm_phase(PG8_LAS unsigned char* lds, const Gemm g, const Sched& S, const Epi& E) {
;     ...
;         const bool has_next = S.next(ui + 1, nxt);
;         const char* nA = has_next ? (const char*)g.A + (size_t)nxt.pm * tstep : cA; const char* nB = has_next ? (const char*)g.Bt + (size_t)nxt.pn * tstep : cB;
;     ...
; #pragma unroll
;         for (int a = 0; a < 2; ++a)
; #pragma unroll
;             for (int b = 0; b < 2; ++b)
; #pragma unroll
;                 for (int m = 0; m < 4; ++m)
; #pragma unroll
;                     for (int n = 0; n < 2; ++n) acc[a][b][m][n] = (f32x4){0.f, 0.f, 0.f, 0.f};
.LBB0_217:
	s_ashr_i32 s41, s40, 31
	s_lshl_b64 s[6:7], s[40:41], 19
	s_add_u32 s46, s22, s6
	s_load_dwordx2 s[48:49], s[0:1], 0xd0
	s_addc_u32 s47, s23, s7
	s_and_b64 s[6:7], s[42:43], exec
	s_cselect_b32 s4, s47, s53
	s_cselect_b32 s41, s46, s52
	s_ashr_i32 s39, s38, 31
	s_lshl_b64 s[6:7], s[38:39], 19
	s_waitcnt lgkmcnt(0)
	s_add_u32 s48, s48, s6
	s_addc_u32 s49, s49, s7
	s_and_b64 s[6:7], s[42:43], exec
	s_cselect_b32 s39, s49, s55
	s_cselect_b32 s78, s48, s54
	s_add_u32 s52, s52, 0x40080
	s_addc_u32 s53, s53, 0
	s_add_u32 s79, s54, 0x100
	v_mov_b32_e32 v0, 0
	s_addc_u32 s33, s55, 0
	s_mov_b32 s72, -2
	v_mov_b32_e32 v1, v0
	v_mov_b32_e32 v2, v0
	v_mov_b32_e32 v3, v0
	v_mov_b32_e32 v8, v0
	v_mov_b32_e32 v9, v0
	v_mov_b32_e32 v10, v0
	v_mov_b32_e32 v11, v0
	v_mov_b32_e32 v16, v0
	v_mov_b32_e32 v17, v0
	v_mov_b32_e32 v18, v0
	v_mov_b32_e32 v19, v0
	v_mov_b32_e32 v24, v0
	v_mov_b32_e32 v25, v0
	v_mov_b32_e32 v26, v0
	v_mov_b32_e32 v27, v0
	v_mov_b32_e32 v32, v0
	v_mov_b32_e32 v33, v0
	v_mov_b32_e32 v34, v0
	v_mov_b32_e32 v35, v0
	v_mov_b32_e32 v40, v0
	v_mov_b32_e32 v41, v0
	v_mov_b32_e32 v42, v0
	v_mov_b32_e32 v43, v0
	v_mov_b32_e32 v48, v0
	v_mov_b32_e32 v49, v0
	v_mov_b32_e32 v50, v0
	v_mov_b32_e32 v51, v0
	v_mov_b32_e32 v56, v0
	v_mov_b32_e32 v57, v0
	v_mov_b32_e32 v58, v0
	v_mov_b32_e32 v59, v0
	v_mov_b32_e32 v4, v0
	v_mov_b32_e32 v5, v0
	v_mov_b32_e32 v6, v0
	v_mov_b32_e32 v7, v0
	v_mov_b32_e32 v12, v0
	v_mov_b32_e32 v13, v0
	v_mov_b32_e32 v14, v0
	v_mov_b32_e32 v15, v0
	v_mov_b32_e32 v20, v0
	v_mov_b32_e32 v21, v0
	v_mov_b32_e32 v22, v0
	v_mov_b32_e32 v23, v0
	v_mov_b32_e32 v28, v0
	v_mov_b32_e32 v29, v0
	v_mov_b32_e32 v30, v0
	v_mov_b32_e32 v31, v0
	v_mov_b32_e32 v36, v0
	v_mov_b32_e32 v37, v0
	v_mov_b32_e32 v38, v0
	v_mov_b32_e32 v39, v0
	v_mov_b32_e32 v44, v0
	v_mov_b32_e32 v45, v0
	v_mov_b32_e32 v46, v0
	v_mov_b32_e32 v47, v0
	v_mov_b32_e32 v52, v0
	v_mov_b32_e32 v53, v0
	v_mov_b32_e32 v54, v0
	v_mov_b32_e32 v55, v0
	v_mov_b32_e32 v60, v0
	v_mov_b32_e32 v61, v0
	v_mov_b32_e32 v62, v0
	v_mov_b32_e32 v63, v0
	v_mov_b32_e32 v64, v0
	v_mov_b32_e32 v65, v0
	v_mov_b32_e32 v66, v0
	v_mov_b32_e32 v67, v0
	v_mov_b32_e32 v72, v0
	v_mov_b32_e32 v73, v0
	v_mov_b32_e32 v74, v0
	v_mov_b32_e32 v75, v0
	v_mov_b32_e32 v80, v0
	v_mov_b32_e32 v81, v0
	v_mov_b32_e32 v82, v0
	v_mov_b32_e32 v83, v0
	v_mov_b32_e32 v88, v0
	v_mov_b32_e32 v89, v0
	v_mov_b32_e32 v90, v0
	v_mov_b32_e32 v91, v0
	v_mov_b32_e32 v96, v0
	v_mov_b32_e32 v97, v0
	v_mov_b32_e32 v98, v0
	v_mov_b32_e32 v99, v0
	v_mov_b32_e32 v104, v0
	v_mov_b32_e32 v105, v0
	v_mov_b32_e32 v106, v0
	v_mov_b32_e32 v107, v0
	v_mov_b32_e32 v112, v0
	v_mov_b32_e32 v113, v0
	v_mov_b32_e32 v114, v0
	v_mov_b32_e32 v115, v0
	v_mov_b32_e32 v120, v0
	v_mov_b32_e32 v121, v0
	v_mov_b32_e32 v122, v0
	v_mov_b32_e32 v123, v0
	v_mov_b32_e32 v68, v0
	v_mov_b32_e32 v69, v0
	v_mov_b32_e32 v70, v0
	v_mov_b32_e32 v71, v0
	v_mov_b32_e32 v76, v0
	v_mov_b32_e32 v77, v0
	v_mov_b32_e32 v78, v0
	v_mov_b32_e32 v79, v0
	v_mov_b32_e32 v84, v0
	v_mov_b32_e32 v85, v0
	v_mov_b32_e32 v86, v0
	v_mov_b32_e32 v87, v0
	v_mov_b32_e32 v92, v0
	v_mov_b32_e32 v93, v0
	v_mov_b32_e32 v94, v0
	v_mov_b32_e32 v95, v0
	v_mov_b32_e32 v100, v0
	v_mov_b32_e32 v101, v0
	v_mov_b32_e32 v102, v0
	v_mov_b32_e32 v103, v0
	v_mov_b32_e32 v108, v0
	v_mov_b32_e32 v109, v0
	v_mov_b32_e32 v110, v0
	v_mov_b32_e32 v111, v0
	v_mov_b32_e32 v116, v0
	v_mov_b32_e32 v117, v0
	v_mov_b32_e32 v118, v0
	v_mov_b32_e32 v119, v0
	v_mov_b32_e32 v124, v0
	v_mov_b32_e32 v125, v0
	v_mov_b32_e32 v126, v0
	v_mov_b32_e32 v127, v0
	.p2align	6

; template <class Epi, class Sched, bool ALIGN_EPI = false, bool SP2 = false>
; __device__ __forceinline__ void gemm_phase(PG8_LAS unsigned char* lds, const Gemm g, const Sched& S, const Epi& E) {
;     ...
;         for (int t = 0; t < nt; t += 2) {
;             const bool last = (t == nt - 2);
;             const char* a1 = cA + (size_t)(t + 1) * kstep;
;             const char* a2 = last ? nA : cA + (size_t)(t + 2) * kstep; const char* b2 = last ? nB : cB + (size_t)(t + 2) * kstep;
;             const char* a3 = a2 + kstep; const char* b3 = b2 + kstep;
;     ...
; #pragma unroll
;         for (int a = 0; a < 2; ++a)
; #pragma unroll
;             for (int b = 0; b < 2; ++b)
; #pragma unroll
;                 for (int m = 0; m < 4; ++m)
; #pragma unroll
;                     for (int n = 0; n < 2; ++n) acc[a][b][m][n] = (f32x4){0.f, 0.f, 0.f, 0.f};
.LBB0_322:
	s_add_u32 s4, s56, 0x100
	v_mov_b32_e32 v0, 0
	s_addc_u32 s33, s57, 0
	s_mov_b32 s69, -2
	s_waitcnt lgkmcnt(0)
	v_mov_b32_e32 v1, v0
	v_mov_b32_e32 v2, v0
	v_mov_b32_e32 v3, v0
	v_mov_b32_e32 v4, v0
	v_mov_b32_e32 v5, v0
	v_mov_b32_e32 v6, v0
	v_mov_b32_e32 v7, v0
	v_mov_b32_e32 v16, v0
	v_mov_b32_e32 v17, v0
	v_mov_b32_e32 v18, v0
	v_mov_b32_e32 v19, v0
	v_mov_b32_e32 v20, v0
	v_mov_b32_e32 v21, v0
	v_mov_b32_e32 v22, v0
	v_mov_b32_e32 v23, v0
	v_mov_b32_e32 v32, v0
	v_mov_b32_e32 v33, v0
	v_mov_b32_e32 v34, v0
	v_mov_b32_e32 v35, v0
	v_mov_b32_e32 v36, v0
	v_mov_b32_e32 v37, v0
	v_mov_b32_e32 v38, v0
	v_mov_b32_e32 v39, v0
	v_mov_b32_e32 v48, v0
	v_mov_b32_e32 v49, v0
	v_mov_b32_e32 v50, v0
	v_mov_b32_e32 v51, v0
	v_mov_b32_e32 v52, v0
	v_mov_b32_e32 v53, v0
	v_mov_b32_e32 v54, v0
	v_mov_b32_e32 v55, v0
	v_mov_b32_e32 v8, v0
	v_mov_b32_e32 v9, v0
	v_mov_b32_e32 v10, v0
	v_mov_b32_e32 v11, v0
	v_mov_b32_e32 v12, v0
	v_mov_b32_e32 v13, v0
	v_mov_b32_e32 v14, v0
	v_mov_b32_e32 v15, v0
	v_mov_b32_e32 v24, v0
	v_mov_b32_e32 v25, v0
	v_mov_b32_e32 v26, v0
	v_mov_b32_e32 v27, v0
	v_mov_b32_e32 v28, v0
	v_mov_b32_e32 v29, v0
	v_mov_b32_e32 v30, v0
	v_mov_b32_e32 v31, v0
	v_mov_b32_e32 v40, v0
	v_mov_b32_e32 v41, v0
	v_mov_b32_e32 v42, v0
	v_mov_b32_e32 v43, v0
	v_mov_b32_e32 v44, v0
	v_mov_b32_e32 v45, v0
	v_mov_b32_e32 v46, v0
	v_mov_b32_e32 v47, v0
	v_mov_b32_e32 v56, v0
	v_mov_b32_e32 v57, v0
	v_mov_b32_e32 v58, v0
	v_mov_b32_e32 v59, v0
	v_mov_b32_e32 v60, v0
	v_mov_b32_e32 v61, v0
	v_mov_b32_e32 v62, v0
	v_mov_b32_e32 v63, v0
	v_mov_b32_e32 v64, v0
	v_mov_b32_e32 v65, v0
	v_mov_b32_e32 v66, v0
	v_mov_b32_e32 v67, v0
	v_mov_b32_e32 v68, v0
	v_mov_b32_e32 v69, v0
	v_mov_b32_e32 v70, v0
	v_mov_b32_e32 v71, v0
	v_mov_b32_e32 v80, v0
	v_mov_b32_e32 v81, v0
	v_mov_b32_e32 v82, v0
	v_mov_b32_e32 v83, v0
	v_mov_b32_e32 v84, v0
	v_mov_b32_e32 v85, v0
	v_mov_b32_e32 v86, v0
	v_mov_b32_e32 v87, v0
	v_mov_b32_e32 v96, v0
	v_mov_b32_e32 v97, v0
	v_mov_b32_e32 v98, v0
	v_mov_b32_e32 v99, v0
	v_mov_b32_e32 v100, v0
	v_mov_b32_e32 v101, v0
	v_mov_b32_e32 v102, v0
	v_mov_b32_e32 v103, v0
	v_mov_b32_e32 v112, v0
	v_mov_b32_e32 v113, v0
	v_mov_b32_e32 v114, v0
	v_mov_b32_e32 v115, v0
	v_mov_b32_e32 v116, v0
	v_mov_b32_e32 v117, v0
	v_mov_b32_e32 v118, v0
	v_mov_b32_e32 v119, v0
	v_mov_b32_e32 v72, v0
	v_mov_b32_e32 v73, v0
	v_mov_b32_e32 v74, v0
	v_mov_b32_e32 v75, v0
	v_mov_b32_e32 v76, v0
	v_mov_b32_e32 v77, v0
	v_mov_b32_e32 v78, v0
	v_mov_b32_e32 v79, v0
	v_mov_b32_e32 v88, v0
	v_mov_b32_e32 v89, v0
	v_mov_b32_e32 v90, v0
	v_mov_b32_e32 v91, v0
	v_mov_b32_e32 v92, v0
	v_mov_b32_e32 v93, v0
	v_mov_b32_e32 v94, v0
	v_mov_b32_e32 v95, v0
	v_mov_b32_e32 v104, v0
	v_mov_b32_e32 v105, v0
	v_mov_b32_e32 v106, v0
	v_mov_b32_e32 v107, v0
	v_mov_b32_e32 v108, v0
	v_mov_b32_e32 v109, v0
	v_mov_b32_e32 v110, v0
	v_mov_b32_e32 v111, v0
	v_mov_b32_e32 v120, v0
	v_mov_b32_e32 v121, v0
	v_mov_b32_e32 v122, v0
	v_mov_b32_e32 v123, v0
	v_mov_b32_e32 v124, v0
	v_mov_b32_e32 v125, v0
	v_mov_b32_e32 v126, v0
	v_mov_b32_e32 v127, v0
	.p2align	6

; template <class Epi, class Sched, bool ALIGN_EPI = false, bool SP2 = false>
; __device__ __forceinline__ void gemm_phase(PG8_LAS unsigned char* lds, const Gemm g, const Sched& S, const Epi& E) {
;     ...
;         const bool has_next = S.next(ui + 1, nxt);
;         const char* nA = has_next ? (const char*)g.A + (size_t)nxt.pm * tstep : cA; const char* nB = has_next ? (const char*)g.Bt + (size_t)nxt.pn * tstep : cB;
;     ...
; #pragma unroll
;         for (int a = 0; a < 2; ++a)
; #pragma unroll
;             for (int b = 0; b < 2; ++b)
; #pragma unroll
;                 for (int m = 0; m < 4; ++m)
; #pragma unroll
;                     for (int n = 0; n < 2; ++n) acc[a][b][m][n] = (f32x4){0.f, 0.f, 0.f, 0.f};
.LBB0_462:
	s_ashr_i32 s55, s54, 31
	s_lshl_b64 s[56:57], s[54:55], 19
	s_add_u32 s56, s22, s56
	s_addc_u32 s57, s23, s57
	s_and_b64 s[58:59], s[46:47], exec
	s_cselect_b32 s49, s57, s61
	s_cselect_b32 s55, s56, s60
	s_ashr_i32 s53, s52, 31
	s_lshl_b64 s[58:59], s[52:53], 19
	s_add_u32 s58, s26, s58
	s_addc_u32 s59, s27, s59
	s_and_b64 s[72:73], s[46:47], exec
	s_cselect_b32 s53, s59, s79
	s_cselect_b32 vcc_lo, s58, s78
	s_add_u32 s60, s60, 0x40080
	s_addc_u32 s61, s61, 0
	s_add_u32 vcc_hi, s78, 0x100
	v_mov_b32_e32 v0, 0
	s_addc_u32 s33, s79, 0
	s_mov_b32 s72, -2
	v_mov_b32_e32 v1, v0
	v_mov_b32_e32 v2, v0
	v_mov_b32_e32 v3, v0
	v_mov_b32_e32 v4, v0
	v_mov_b32_e32 v5, v0
	v_mov_b32_e32 v6, v0
	v_mov_b32_e32 v7, v0
	v_mov_b32_e32 v16, v0
	v_mov_b32_e32 v17, v0
	v_mov_b32_e32 v18, v0
	v_mov_b32_e32 v19, v0
	v_mov_b32_e32 v20, v0
	v_mov_b32_e32 v21, v0
	v_mov_b32_e32 v22, v0
	v_mov_b32_e32 v23, v0
	v_mov_b32_e32 v32, v0
	v_mov_b32_e32 v33, v0
	v_mov_b32_e32 v34, v0
	v_mov_b32_e32 v35, v0
	v_mov_b32_e32 v36, v0
	v_mov_b32_e32 v37, v0
	v_mov_b32_e32 v38, v0
	v_mov_b32_e32 v39, v0
	v_mov_b32_e32 v48, v0
	v_mov_b32_e32 v49, v0
	v_mov_b32_e32 v50, v0
	v_mov_b32_e32 v51, v0
	v_mov_b32_e32 v52, v0
	v_mov_b32_e32 v53, v0
	v_mov_b32_e32 v54, v0
	v_mov_b32_e32 v55, v0
	v_mov_b32_e32 v8, v0
	v_mov_b32_e32 v9, v0
	v_mov_b32_e32 v10, v0
	v_mov_b32_e32 v11, v0
	v_mov_b32_e32 v12, v0
	v_mov_b32_e32 v13, v0
	v_mov_b32_e32 v14, v0
	v_mov_b32_e32 v15, v0
	v_mov_b32_e32 v24, v0
	v_mov_b32_e32 v25, v0
	v_mov_b32_e32 v26, v0
	v_mov_b32_e32 v27, v0
	v_mov_b32_e32 v28, v0
	v_mov_b32_e32 v29, v0
	v_mov_b32_e32 v30, v0
	v_mov_b32_e32 v31, v0
	v_mov_b32_e32 v40, v0
	v_mov_b32_e32 v41, v0
	v_mov_b32_e32 v42, v0
	v_mov_b32_e32 v43, v0
	v_mov_b32_e32 v44, v0
	v_mov_b32_e32 v45, v0
	v_mov_b32_e32 v46, v0
	v_mov_b32_e32 v47, v0
	v_mov_b32_e32 v56, v0
	v_mov_b32_e32 v57, v0
	v_mov_b32_e32 v58, v0
	v_mov_b32_e32 v59, v0
	v_mov_b32_e32 v60, v0
	v_mov_b32_e32 v61, v0
	v_mov_b32_e32 v62, v0
	v_mov_b32_e32 v63, v0
	v_mov_b32_e32 v64, v0
	v_mov_b32_e32 v65, v0
	v_mov_b32_e32 v66, v0
	v_mov_b32_e32 v67, v0
	v_mov_b32_e32 v68, v0
	v_mov_b32_e32 v69, v0
	v_mov_b32_e32 v70, v0
	v_mov_b32_e32 v71, v0
	v_mov_b32_e32 v80, v0
	v_mov_b32_e32 v81, v0
	v_mov_b32_e32 v82, v0
	v_mov_b32_e32 v83, v0
	v_mov_b32_e32 v84, v0
	v_mov_b32_e32 v85, v0
	v_mov_b32_e32 v86, v0
	v_mov_b32_e32 v87, v0
	v_mov_b32_e32 v96, v0
	v_mov_b32_e32 v97, v0
	v_mov_b32_e32 v98, v0
	v_mov_b32_e32 v99, v0
	v_mov_b32_e32 v100, v0
	v_mov_b32_e32 v101, v0
	v_mov_b32_e32 v102, v0
	v_mov_b32_e32 v103, v0
	v_mov_b32_e32 v112, v0
	v_mov_b32_e32 v113, v0
	v_mov_b32_e32 v114, v0
	v_mov_b32_e32 v115, v0
	v_mov_b32_e32 v116, v0
	v_mov_b32_e32 v117, v0
	v_mov_b32_e32 v118, v0
	v_mov_b32_e32 v119, v0
	v_mov_b32_e32 v72, v0
	v_mov_b32_e32 v73, v0
	v_mov_b32_e32 v74, v0
	v_mov_b32_e32 v75, v0
	v_mov_b32_e32 v76, v0
	v_mov_b32_e32 v77, v0
	v_mov_b32_e32 v78, v0
	v_mov_b32_e32 v79, v0
	v_mov_b32_e32 v88, v0
	v_mov_b32_e32 v89, v0
	v_mov_b32_e32 v90, v0
	v_mov_b32_e32 v91, v0
	v_mov_b32_e32 v92, v0
	v_mov_b32_e32 v93, v0
	v_mov_b32_e32 v94, v0
	v_mov_b32_e32 v95, v0
	v_mov_b32_e32 v104, v0
	v_mov_b32_e32 v105, v0
	v_mov_b32_e32 v106, v0
	v_mov_b32_e32 v107, v0
	v_mov_b32_e32 v108, v0
	v_mov_b32_e32 v109, v0
	v_mov_b32_e32 v110, v0
	v_mov_b32_e32 v111, v0
	v_mov_b32_e32 v120, v0
	v_mov_b32_e32 v121, v0
	v_mov_b32_e32 v122, v0
	v_mov_b32_e32 v123, v0
	v_mov_b32_e32 v124, v0
	v_mov_b32_e32 v125, v0
	v_mov_b32_e32 v126, v0
	v_mov_b32_e32 v127, v0
	.p2align	6

; template <class Epi, class Sched, bool ALIGN_EPI = false, bool SP2 = false>
; __device__ __forceinline__ void gemm_phase(PG8_LAS unsigned char* lds, const Gemm g, const Sched& S, const Epi& E) {
;     ...
;         for (int t = 0; t < nt; t += 2) {
;             const bool last = (t == nt - 2);
;             const char* a1 = cA + (size_t)(t + 1) * kstep;
;             const char* a2 = last ? nA : cA + (size_t)(t + 2) * kstep; const char* b2 = last ? nB : cB + (size_t)(t + 2) * kstep;
;             const char* a3 = a2 + kstep; const char* b3 = b2 + kstep;
;     ...
; #pragma unroll
;         for (int a = 0; a < 2; ++a)
; #pragma unroll
;             for (int b = 0; b < 2; ++b)
; #pragma unroll
;                 for (int m = 0; m < 4; ++m)
; #pragma unroll
;                     for (int n = 0; n < 2; ++n) acc[a][b][m][n] = (f32x4){0.f, 0.f, 0.f, 0.f};
.LBB0_776:
	s_add_u32 s33, s60, 0x100
	v_mov_b32_e32 v0, 0
	s_addc_u32 vcc_lo, s61, 0
	s_mov_b32 s72, -2
	s_waitcnt lgkmcnt(0)
	v_mov_b32_e32 v1, v0
	v_mov_b32_e32 v2, v0
	v_mov_b32_e32 v3, v0
	v_mov_b32_e32 v4, v0
	v_mov_b32_e32 v5, v0
	v_mov_b32_e32 v6, v0
	v_mov_b32_e32 v7, v0
	v_mov_b32_e32 v16, v0
	v_mov_b32_e32 v17, v0
	v_mov_b32_e32 v18, v0
	v_mov_b32_e32 v19, v0
	v_mov_b32_e32 v20, v0
	v_mov_b32_e32 v21, v0
	v_mov_b32_e32 v22, v0
	v_mov_b32_e32 v23, v0
	v_mov_b32_e32 v32, v0
	v_mov_b32_e32 v33, v0
	v_mov_b32_e32 v34, v0
	v_mov_b32_e32 v35, v0
	v_mov_b32_e32 v36, v0
	v_mov_b32_e32 v37, v0
	v_mov_b32_e32 v38, v0
	v_mov_b32_e32 v39, v0
	v_mov_b32_e32 v48, v0
	v_mov_b32_e32 v49, v0
	v_mov_b32_e32 v50, v0
	v_mov_b32_e32 v51, v0
	v_mov_b32_e32 v52, v0
	v_mov_b32_e32 v53, v0
	v_mov_b32_e32 v54, v0
	v_mov_b32_e32 v55, v0
	v_mov_b32_e32 v8, v0
	v_mov_b32_e32 v9, v0
	v_mov_b32_e32 v10, v0
	v_mov_b32_e32 v11, v0
	v_mov_b32_e32 v12, v0
	v_mov_b32_e32 v13, v0
	v_mov_b32_e32 v14, v0
	v_mov_b32_e32 v15, v0
	v_mov_b32_e32 v24, v0
	v_mov_b32_e32 v25, v0
	v_mov_b32_e32 v26, v0
	v_mov_b32_e32 v27, v0
	v_mov_b32_e32 v28, v0
	v_mov_b32_e32 v29, v0
	v_mov_b32_e32 v30, v0
	v_mov_b32_e32 v31, v0
	v_mov_b32_e32 v40, v0
	v_mov_b32_e32 v41, v0
	v_mov_b32_e32 v42, v0
	v_mov_b32_e32 v43, v0
	v_mov_b32_e32 v44, v0
	v_mov_b32_e32 v45, v0
	v_mov_b32_e32 v46, v0
	v_mov_b32_e32 v47, v0
	v_mov_b32_e32 v56, v0
	v_mov_b32_e32 v57, v0
	v_mov_b32_e32 v58, v0
	v_mov_b32_e32 v59, v0
	v_mov_b32_e32 v60, v0
	v_mov_b32_e32 v61, v0
	v_mov_b32_e32 v62, v0
	v_mov_b32_e32 v63, v0
	v_mov_b32_e32 v64, v0
	v_mov_b32_e32 v65, v0
	v_mov_b32_e32 v66, v0
	v_mov_b32_e32 v67, v0
	v_mov_b32_e32 v68, v0
	v_mov_b32_e32 v69, v0
	v_mov_b32_e32 v70, v0
	v_mov_b32_e32 v71, v0
	v_mov_b32_e32 v80, v0
	v_mov_b32_e32 v81, v0
	v_mov_b32_e32 v82, v0
	v_mov_b32_e32 v83, v0
	v_mov_b32_e32 v84, v0
	v_mov_b32_e32 v85, v0
	v_mov_b32_e32 v86, v0
	v_mov_b32_e32 v87, v0
	v_mov_b32_e32 v96, v0
	v_mov_b32_e32 v97, v0
	v_mov_b32_e32 v98, v0
	v_mov_b32_e32 v99, v0
	v_mov_b32_e32 v100, v0
	v_mov_b32_e32 v101, v0
	v_mov_b32_e32 v102, v0
	v_mov_b32_e32 v103, v0
	v_mov_b32_e32 v112, v0
	v_mov_b32_e32 v113, v0
	v_mov_b32_e32 v114, v0
	v_mov_b32_e32 v115, v0
	v_mov_b32_e32 v116, v0
	v_mov_b32_e32 v117, v0
	v_mov_b32_e32 v118, v0
	v_mov_b32_e32 v119, v0
	v_mov_b32_e32 v72, v0
	v_mov_b32_e32 v73, v0
	v_mov_b32_e32 v74, v0
	v_mov_b32_e32 v75, v0
	v_mov_b32_e32 v76, v0
	v_mov_b32_e32 v77, v0
	v_mov_b32_e32 v78, v0
	v_mov_b32_e32 v79, v0
	v_mov_b32_e32 v88, v0
	v_mov_b32_e32 v89, v0
	v_mov_b32_e32 v90, v0
	v_mov_b32_e32 v91, v0
	v_mov_b32_e32 v92, v0
	v_mov_b32_e32 v93, v0
	v_mov_b32_e32 v94, v0
	v_mov_b32_e32 v95, v0
	v_mov_b32_e32 v104, v0
	v_mov_b32_e32 v105, v0
	v_mov_b32_e32 v106, v0
	v_mov_b32_e32 v107, v0
	v_mov_b32_e32 v108, v0
	v_mov_b32_e32 v109, v0
	v_mov_b32_e32 v110, v0
	v_mov_b32_e32 v111, v0
	v_mov_b32_e32 v120, v0
	v_mov_b32_e32 v121, v0
	v_mov_b32_e32 v122, v0
	v_mov_b32_e32 v123, v0
	v_mov_b32_e32 v124, v0
	v_mov_b32_e32 v125, v0
	v_mov_b32_e32 v126, v0
	v_mov_b32_e32 v127, v0
	.p2align	6

; template <class Epi, class Sched, bool ALIGN_EPI = false, bool SP2 = false>
; __device__ __forceinline__ void gemm_phase(PG8_LAS unsigned char* lds, const Gemm g, const Sched& S, const Epi& E) {
;     ...
;         const bool has_next = S.next(ui + 1, nxt);
;         const char* nA = has_next ? (const char*)g.A + (size_t)nxt.pm * tstep : cA; const char* nB = has_next ? (const char*)g.Bt + (size_t)nxt.pn * tstep : cB;
;     ...
; #pragma unroll
;         for (int a = 0; a < 2; ++a)
; #pragma unroll
;             for (int b = 0; b < 2; ++b)
; #pragma unroll
;                 for (int m = 0; m < 4; ++m)
; #pragma unroll
;                     for (int n = 0; n < 2; ++n) acc[a][b][m][n] = (f32x4){0.f, 0.f, 0.f, 0.f};
.LBB0_900:
	s_ashr_i32 s49, s48, 31
	s_lshl_b64 s[6:7], s[48:49], 19
	s_add_u32 s50, s22, s6
	s_addc_u32 s51, s23, s7
	s_and_b64 s[6:7], s[46:47], exec
	s_cselect_b32 s49, s51, s57
	s_cselect_b32 s76, s50, s56
	s_ashr_i32 s41, s40, 31
	s_lshl_b64 s[6:7], s[40:41], 19
	s_add_u32 s52, s4, s6
	s_addc_u32 s53, s26, s7
	s_and_b64 s[6:7], s[46:47], exec
	s_cselect_b32 s41, s53, s59
	s_cselect_b32 s77, s52, s58
	s_add_u32 s56, s56, 0x40080
	s_addc_u32 s57, s57, 0
	s_add_u32 s78, s58, 0x100
	v_mov_b32_e32 v0, 0
	s_addc_u32 s33, s59, 0
	s_mov_b32 s72, -2
	v_mov_b32_e32 v1, v0
	v_mov_b32_e32 v2, v0
	v_mov_b32_e32 v3, v0
	v_mov_b32_e32 v8, v0
	v_mov_b32_e32 v9, v0
	v_mov_b32_e32 v10, v0
	v_mov_b32_e32 v11, v0
	v_mov_b32_e32 v16, v0
	v_mov_b32_e32 v17, v0
	v_mov_b32_e32 v18, v0
	v_mov_b32_e32 v19, v0
	v_mov_b32_e32 v24, v0
	v_mov_b32_e32 v25, v0
	v_mov_b32_e32 v26, v0
	v_mov_b32_e32 v27, v0
	v_mov_b32_e32 v32, v0
	v_mov_b32_e32 v33, v0
	v_mov_b32_e32 v34, v0
	v_mov_b32_e32 v35, v0
	v_mov_b32_e32 v40, v0
	v_mov_b32_e32 v41, v0
	v_mov_b32_e32 v42, v0
	v_mov_b32_e32 v43, v0
	v_mov_b32_e32 v48, v0
	v_mov_b32_e32 v49, v0
	v_mov_b32_e32 v50, v0
	v_mov_b32_e32 v51, v0
	v_mov_b32_e32 v56, v0
	v_mov_b32_e32 v57, v0
	v_mov_b32_e32 v58, v0
	v_mov_b32_e32 v59, v0
	v_mov_b32_e32 v4, v0
	v_mov_b32_e32 v5, v0
	v_mov_b32_e32 v6, v0
	v_mov_b32_e32 v7, v0
	v_mov_b32_e32 v12, v0
	v_mov_b32_e32 v13, v0
	v_mov_b32_e32 v14, v0
	v_mov_b32_e32 v15, v0
	v_mov_b32_e32 v20, v0
	v_mov_b32_e32 v21, v0
	v_mov_b32_e32 v22, v0
	v_mov_b32_e32 v23, v0
	v_mov_b32_e32 v28, v0
	v_mov_b32_e32 v29, v0
	v_mov_b32_e32 v30, v0
	v_mov_b32_e32 v31, v0
	v_mov_b32_e32 v36, v0
	v_mov_b32_e32 v37, v0
	v_mov_b32_e32 v38, v0
	v_mov_b32_e32 v39, v0
	v_mov_b32_e32 v44, v0
	v_mov_b32_e32 v45, v0
	v_mov_b32_e32 v46, v0
	v_mov_b32_e32 v47, v0
	v_mov_b32_e32 v52, v0
	v_mov_b32_e32 v53, v0
	v_mov_b32_e32 v54, v0
	v_mov_b32_e32 v55, v0
	v_mov_b32_e32 v60, v0
	v_mov_b32_e32 v61, v0
	v_mov_b32_e32 v62, v0
	v_mov_b32_e32 v63, v0
	v_mov_b32_e32 v64, v0
	v_mov_b32_e32 v65, v0
	v_mov_b32_e32 v66, v0
	v_mov_b32_e32 v67, v0
	v_mov_b32_e32 v72, v0
	v_mov_b32_e32 v73, v0
	v_mov_b32_e32 v74, v0
	v_mov_b32_e32 v75, v0
	v_mov_b32_e32 v80, v0
	v_mov_b32_e32 v81, v0
	v_mov_b32_e32 v82, v0
	v_mov_b32_e32 v83, v0
	v_mov_b32_e32 v88, v0
	v_mov_b32_e32 v89, v0
	v_mov_b32_e32 v90, v0
	v_mov_b32_e32 v91, v0
	v_mov_b32_e32 v96, v0
	v_mov_b32_e32 v97, v0
	v_mov_b32_e32 v98, v0
	v_mov_b32_e32 v99, v0
	v_mov_b32_e32 v104, v0
	v_mov_b32_e32 v105, v0
	v_mov_b32_e32 v106, v0
	v_mov_b32_e32 v107, v0
	v_mov_b32_e32 v112, v0
	v_mov_b32_e32 v113, v0
	v_mov_b32_e32 v114, v0
	v_mov_b32_e32 v115, v0
	v_mov_b32_e32 v120, v0
	v_mov_b32_e32 v121, v0
	v_mov_b32_e32 v122, v0
	v_mov_b32_e32 v123, v0
	v_mov_b32_e32 v68, v0
	v_mov_b32_e32 v69, v0
	v_mov_b32_e32 v70, v0
	v_mov_b32_e32 v71, v0
	v_mov_b32_e32 v76, v0
	v_mov_b32_e32 v77, v0
	v_mov_b32_e32 v78, v0
	v_mov_b32_e32 v79, v0
	v_mov_b32_e32 v84, v0
	v_mov_b32_e32 v85, v0
	v_mov_b32_e32 v86, v0
	v_mov_b32_e32 v87, v0
	v_mov_b32_e32 v92, v0
	v_mov_b32_e32 v93, v0
	v_mov_b32_e32 v94, v0
	v_mov_b32_e32 v95, v0
	v_mov_b32_e32 v100, v0
	v_mov_b32_e32 v101, v0
	v_mov_b32_e32 v102, v0
	v_mov_b32_e32 v103, v0
	v_mov_b32_e32 v108, v0
	v_mov_b32_e32 v109, v0
	v_mov_b32_e32 v110, v0
	v_mov_b32_e32 v111, v0
	v_mov_b32_e32 v116, v0
	v_mov_b32_e32 v117, v0
	v_mov_b32_e32 v118, v0
	v_mov_b32_e32 v119, v0
	v_mov_b32_e32 v124, v0
	v_mov_b32_e32 v125, v0
	v_mov_b32_e32 v126, v0
	v_mov_b32_e32 v127, v0
	.p2align	6

; template <class Epi, class Sched, bool ALIGN_EPI = false, bool SP2 = false>
; __device__ __forceinline__ void gemm_phase(PG8_LAS unsigned char* lds, const Gemm g, const Sched& S, const Epi& E) {
;     ...
;         for (int t = 0; t < nt; t += 2) {
;             const bool last = (t == nt - 2);
;             const char* a1 = cA + (size_t)(t + 1) * kstep;
;             const char* a2 = last ? nA : cA + (size_t)(t + 2) * kstep; const char* b2 = last ? nB : cB + (size_t)(t + 2) * kstep;
;             const char* a3 = a2 + kstep; const char* b3 = b2 + kstep;
;     ...
; #pragma unroll
;         for (int a = 0; a < 2; ++a)
; #pragma unroll
;             for (int b = 0; b < 2; ++b)
; #pragma unroll
;                 for (int m = 0; m < 4; ++m)
; #pragma unroll
;                     for (int n = 0; n < 2; ++n) acc[a][b][m][n] = (f32x4){0.f, 0.f, 0.f, 0.f};
.LBB0_1013:
	s_add_u32 s33, s58, 0x100
	v_mov_b32_e32 v0, 0
	s_addc_u32 s80, s59, 0
	s_mov_b32 s72, -2
	s_waitcnt lgkmcnt(0)
	v_mov_b32_e32 v1, v0
	v_mov_b32_e32 v2, v0
	v_mov_b32_e32 v3, v0
	v_mov_b32_e32 v4, v0
	v_mov_b32_e32 v5, v0
	v_mov_b32_e32 v6, v0
	v_mov_b32_e32 v7, v0
	v_mov_b32_e32 v16, v0
	v_mov_b32_e32 v17, v0
	v_mov_b32_e32 v18, v0
	v_mov_b32_e32 v19, v0
	v_mov_b32_e32 v20, v0
	v_mov_b32_e32 v21, v0
	v_mov_b32_e32 v22, v0
	v_mov_b32_e32 v23, v0
	v_mov_b32_e32 v32, v0
	v_mov_b32_e32 v33, v0
	v_mov_b32_e32 v34, v0
	v_mov_b32_e32 v35, v0
	v_mov_b32_e32 v36, v0
	v_mov_b32_e32 v37, v0
	v_mov_b32_e32 v38, v0
	v_mov_b32_e32 v39, v0
	v_mov_b32_e32 v48, v0
	v_mov_b32_e32 v49, v0
	v_mov_b32_e32 v50, v0
	v_mov_b32_e32 v51, v0
	v_mov_b32_e32 v52, v0
	v_mov_b32_e32 v53, v0
	v_mov_b32_e32 v54, v0
	v_mov_b32_e32 v55, v0
	v_mov_b32_e32 v8, v0
	v_mov_b32_e32 v9, v0
	v_mov_b32_e32 v10, v0
	v_mov_b32_e32 v11, v0
	v_mov_b32_e32 v12, v0
	v_mov_b32_e32 v13, v0
	v_mov_b32_e32 v14, v0
	v_mov_b32_e32 v15, v0
	v_mov_b32_e32 v24, v0
	v_mov_b32_e32 v25, v0
	v_mov_b32_e32 v26, v0
	v_mov_b32_e32 v27, v0
	v_mov_b32_e32 v28, v0
	v_mov_b32_e32 v29, v0
	v_mov_b32_e32 v30, v0
	v_mov_b32_e32 v31, v0
	v_mov_b32_e32 v40, v0
	v_mov_b32_e32 v41, v0
	v_mov_b32_e32 v42, v0
	v_mov_b32_e32 v43, v0
	v_mov_b32_e32 v44, v0
	v_mov_b32_e32 v45, v0
	v_mov_b32_e32 v46, v0
	v_mov_b32_e32 v47, v0
	v_mov_b32_e32 v56, v0
	v_mov_b32_e32 v57, v0
	v_mov_b32_e32 v58, v0
	v_mov_b32_e32 v59, v0
	v_mov_b32_e32 v60, v0
	v_mov_b32_e32 v61, v0
	v_mov_b32_e32 v62, v0
	v_mov_b32_e32 v63, v0
	v_mov_b32_e32 v64, v0
	v_mov_b32_e32 v65, v0
	v_mov_b32_e32 v66, v0
	v_mov_b32_e32 v67, v0
	v_mov_b32_e32 v68, v0
	v_mov_b32_e32 v69, v0
	v_mov_b32_e32 v70, v0
	v_mov_b32_e32 v71, v0
	v_mov_b32_e32 v80, v0
	v_mov_b32_e32 v81, v0
	v_mov_b32_e32 v82, v0
	v_mov_b32_e32 v83, v0
	v_mov_b32_e32 v84, v0
	v_mov_b32_e32 v85, v0
	v_mov_b32_e32 v86, v0
	v_mov_b32_e32 v87, v0
	v_mov_b32_e32 v96, v0
	v_mov_b32_e32 v97, v0
	v_mov_b32_e32 v98, v0
	v_mov_b32_e32 v99, v0
	v_mov_b32_e32 v100, v0
	v_mov_b32_e32 v101, v0
	v_mov_b32_e32 v102, v0
	v_mov_b32_e32 v103, v0
	v_mov_b32_e32 v112, v0
	v_mov_b32_e32 v113, v0
	v_mov_b32_e32 v114, v0
	v_mov_b32_e32 v115, v0
	v_mov_b32_e32 v116, v0
	v_mov_b32_e32 v117, v0
	v_mov_b32_e32 v118, v0
	v_mov_b32_e32 v119, v0
	v_mov_b32_e32 v72, v0
	v_mov_b32_e32 v73, v0
	v_mov_b32_e32 v74, v0
	v_mov_b32_e32 v75, v0
	v_mov_b32_e32 v76, v0
	v_mov_b32_e32 v77, v0
	v_mov_b32_e32 v78, v0
	v_mov_b32_e32 v79, v0
	v_mov_b32_e32 v88, v0
	v_mov_b32_e32 v89, v0
	v_mov_b32_e32 v90, v0
	v_mov_b32_e32 v91, v0
	v_mov_b32_e32 v92, v0
	v_mov_b32_e32 v93, v0
	v_mov_b32_e32 v94, v0
	v_mov_b32_e32 v95, v0
	v_mov_b32_e32 v104, v0
	v_mov_b32_e32 v105, v0
	v_mov_b32_e32 v106, v0
	v_mov_b32_e32 v107, v0
	v_mov_b32_e32 v108, v0
	v_mov_b32_e32 v109, v0
	v_mov_b32_e32 v110, v0
	v_mov_b32_e32 v111, v0
	v_mov_b32_e32 v120, v0
	v_mov_b32_e32 v121, v0
	v_mov_b32_e32 v122, v0
	v_mov_b32_e32 v123, v0
	v_mov_b32_e32 v124, v0
	v_mov_b32_e32 v125, v0
	v_mov_b32_e32 v126, v0
	v_mov_b32_e32 v127, v0
	.p2align	6

; template <class Epi, class Sched, bool ALIGN_EPI = false, bool SP2 = false>
; __device__ __forceinline__ void gemm_phase(PG8_LAS unsigned char* lds, const Gemm g, const Sched& S, const Epi& E) {
;     ...
;         const bool has_next = S.next(ui + 1, nxt);
;         const char* nA = has_next ? (const char*)g.A + (size_t)nxt.pm * tstep : cA; const char* nB = has_next ? (const char*)g.Bt + (size_t)nxt.pn * tstep : cB;
;     ...
; #pragma unroll
;         for (int a = 0; a < 2; ++a)
; #pragma unroll
;             for (int b = 0; b < 2; ++b)
; #pragma unroll
;                 for (int m = 0; m < 4; ++m)
; #pragma unroll
;                     for (int n = 0; n < 2; ++n) acc[a][b][m][n] = (f32x4){0.f, 0.f, 0.f, 0.f};
.LBB0_1391:
	s_ashr_i32 s51, s50, 31
	s_lshl_b64 s[6:7], s[50:51], 19
	s_add_u32 s52, s22, s6
	s_addc_u32 s53, s23, s7
	s_and_b64 s[6:7], s[46:47], exec
	s_cselect_b32 s51, s53, s59
	s_cselect_b32 s75, s52, s58
	s_ashr_i32 s49, s48, 31
	s_lshl_b64 s[6:7], s[48:49], 19
	s_add_u32 s54, s4, s6
	s_addc_u32 s55, s26, s7
	s_and_b64 s[6:7], s[46:47], exec
	s_cselect_b32 s49, s55, s61
	s_cselect_b32 s76, s54, s60
	s_add_u32 s58, s58, 0x40080
	s_addc_u32 s59, s59, 0
	s_add_u32 s77, s60, 0x100
	v_mov_b32_e32 v0, 0
	s_addc_u32 s33, s61, 0
	s_mov_b32 s72, -2
	v_mov_b32_e32 v1, v0
	v_mov_b32_e32 v2, v0
	v_mov_b32_e32 v3, v0
	v_mov_b32_e32 v4, v0
	v_mov_b32_e32 v5, v0
	v_mov_b32_e32 v6, v0
	v_mov_b32_e32 v7, v0
	v_mov_b32_e32 v12, v0
	v_mov_b32_e32 v13, v0
	v_mov_b32_e32 v14, v0
	v_mov_b32_e32 v15, v0
	v_mov_b32_e32 v16, v0
	v_mov_b32_e32 v17, v0
	v_mov_b32_e32 v18, v0
	v_mov_b32_e32 v19, v0
	v_mov_b32_e32 v28, v0
	v_mov_b32_e32 v29, v0
	v_mov_b32_e32 v30, v0
	v_mov_b32_e32 v31, v0
	v_mov_b32_e32 v32, v0
	v_mov_b32_e32 v33, v0
	v_mov_b32_e32 v34, v0
	v_mov_b32_e32 v35, v0
	v_mov_b32_e32 v44, v0
	v_mov_b32_e32 v45, v0
	v_mov_b32_e32 v46, v0
	v_mov_b32_e32 v47, v0
	v_mov_b32_e32 v48, v0
	v_mov_b32_e32 v49, v0
	v_mov_b32_e32 v50, v0
	v_mov_b32_e32 v51, v0
	v_mov_b32_e32 v8, v0
	v_mov_b32_e32 v9, v0
	v_mov_b32_e32 v10, v0
	v_mov_b32_e32 v11, v0
	v_mov_b32_e32 v20, v0
	v_mov_b32_e32 v21, v0
	v_mov_b32_e32 v22, v0
	v_mov_b32_e32 v23, v0
	v_mov_b32_e32 v24, v0
	v_mov_b32_e32 v25, v0
	v_mov_b32_e32 v26, v0
	v_mov_b32_e32 v27, v0
	v_mov_b32_e32 v36, v0
	v_mov_b32_e32 v37, v0
	v_mov_b32_e32 v38, v0
	v_mov_b32_e32 v39, v0
	v_mov_b32_e32 v40, v0
	v_mov_b32_e32 v41, v0
	v_mov_b32_e32 v42, v0
	v_mov_b32_e32 v43, v0
	v_mov_b32_e32 v52, v0
	v_mov_b32_e32 v53, v0
	v_mov_b32_e32 v54, v0
	v_mov_b32_e32 v55, v0
	v_mov_b32_e32 v56, v0
	v_mov_b32_e32 v57, v0
	v_mov_b32_e32 v58, v0
	v_mov_b32_e32 v59, v0
	v_mov_b32_e32 v60, v0
	v_mov_b32_e32 v61, v0
	v_mov_b32_e32 v62, v0
	v_mov_b32_e32 v63, v0
	v_mov_b32_e32 v64, v0
	v_mov_b32_e32 v65, v0
	v_mov_b32_e32 v66, v0
	v_mov_b32_e32 v67, v0
	v_mov_b32_e32 v68, v0
	v_mov_b32_e32 v69, v0
	v_mov_b32_e32 v70, v0
	v_mov_b32_e32 v71, v0
	v_mov_b32_e32 v76, v0
	v_mov_b32_e32 v77, v0
	v_mov_b32_e32 v78, v0
	v_mov_b32_e32 v79, v0
	v_mov_b32_e32 v84, v0
	v_mov_b32_e32 v85, v0
	v_mov_b32_e32 v86, v0
	v_mov_b32_e32 v87, v0
	v_mov_b32_e32 v92, v0
	v_mov_b32_e32 v93, v0
	v_mov_b32_e32 v94, v0
	v_mov_b32_e32 v95, v0
	v_mov_b32_e32 v100, v0
	v_mov_b32_e32 v101, v0
	v_mov_b32_e32 v102, v0
	v_mov_b32_e32 v103, v0
	v_mov_b32_e32 v108, v0
	v_mov_b32_e32 v109, v0
	v_mov_b32_e32 v110, v0
	v_mov_b32_e32 v111, v0
	v_mov_b32_e32 v116, v0
	v_mov_b32_e32 v117, v0
	v_mov_b32_e32 v118, v0
	v_mov_b32_e32 v119, v0
	v_mov_b32_e32 v72, v0
	v_mov_b32_e32 v73, v0
	v_mov_b32_e32 v74, v0
	v_mov_b32_e32 v75, v0
	v_mov_b32_e32 v80, v0
	v_mov_b32_e32 v81, v0
	v_mov_b32_e32 v82, v0
	v_mov_b32_e32 v83, v0
	v_mov_b32_e32 v88, v0
	v_mov_b32_e32 v89, v0
	v_mov_b32_e32 v90, v0
	v_mov_b32_e32 v91, v0
	v_mov_b32_e32 v96, v0
	v_mov_b32_e32 v97, v0
	v_mov_b32_e32 v98, v0
	v_mov_b32_e32 v99, v0
	v_mov_b32_e32 v104, v0
	v_mov_b32_e32 v105, v0
	v_mov_b32_e32 v106, v0
	v_mov_b32_e32 v107, v0
	v_mov_b32_e32 v112, v0
	v_mov_b32_e32 v113, v0
	v_mov_b32_e32 v114, v0
	v_mov_b32_e32 v115, v0
	v_mov_b32_e32 v120, v0
	v_mov_b32_e32 v121, v0
	v_mov_b32_e32 v122, v0
	v_mov_b32_e32 v123, v0
	v_mov_b32_e32 v124, v0
	v_mov_b32_e32 v125, v0
	v_mov_b32_e32 v126, v0
	v_mov_b32_e32 v127, v0
	.p2align	6

; template <class Epi, class Sched, bool ALIGN_EPI = false, bool SP2 = false>
; __device__ __forceinline__ void gemm_phase(PG8_LAS unsigned char* lds, const Gemm g, const Sched& S, const Epi& E) {
;     ...
;         const bool has_next = S.next(ui + 1, nxt);
;         const char* nA = has_next ? (const char*)g.A + (size_t)nxt.pm * tstep : cA; const char* nB = has_next ? (const char*)g.Bt + (size_t)nxt.pn * tstep : cB;
;     ...
; #pragma unroll
;         for (int a = 0; a < 2; ++a)
; #pragma unroll
;             for (int b = 0; b < 2; ++b)
; #pragma unroll
;                 for (int m = 0; m < 4; ++m)
; #pragma unroll
;                     for (int n = 0; n < 2; ++n) acc[a][b][m][n] = (f32x4){0.f, 0.f, 0.f, 0.f};
.LBB0_1616:
	s_ashr_i32 s51, s50, 31
	s_lshl_b64 s[6:7], s[50:51], 19
	s_add_u32 s52, s34, s6
	s_addc_u32 s53, s35, s7
	s_and_b64 s[6:7], s[46:47], exec
	s_cselect_b32 s26, s53, s57
	s_cselect_b32 s29, s52, s56
	s_ashr_i32 s49, s48, 31
	s_lshl_b64 s[6:7], s[48:49], 19
	s_add_u32 s54, s5, s6
	s_addc_u32 s55, s27, s7
	s_and_b64 s[6:7], s[46:47], exec
	s_cselect_b32 s49, s55, s59
	s_cselect_b32 s51, s54, s58
	s_add_u32 s56, s56, 0x40080
	s_addc_u32 s57, s57, 0
	s_add_u32 s68, s58, 0x100
	v_mov_b32_e32 v0, 0
	s_addc_u32 s33, s59, 0
	s_mov_b32 s69, -2
	v_mov_b32_e32 v1, v0
	v_mov_b32_e32 v2, v0
	v_mov_b32_e32 v3, v0
	v_mov_b32_e32 v4, v0
	v_mov_b32_e32 v5, v0
	v_mov_b32_e32 v6, v0
	v_mov_b32_e32 v7, v0
	v_mov_b32_e32 v16, v0
	v_mov_b32_e32 v17, v0
	v_mov_b32_e32 v18, v0
	v_mov_b32_e32 v19, v0
	v_mov_b32_e32 v20, v0
	v_mov_b32_e32 v21, v0
	v_mov_b32_e32 v22, v0
	v_mov_b32_e32 v23, v0
	s_waitcnt vmcnt(0)
	v_mov_b32_e32 v40, v0
	v_mov_b32_e32 v41, v0
	v_mov_b32_e32 v42, v0
	v_mov_b32_e32 v43, v0
	v_mov_b32_e32 v44, v0
	v_mov_b32_e32 v45, v0
	v_mov_b32_e32 v46, v0
	v_mov_b32_e32 v47, v0
	v_mov_b32_e32 v64, v0
	v_mov_b32_e32 v65, v0
	v_mov_b32_e32 v66, v0
	v_mov_b32_e32 v67, v0
	v_mov_b32_e32 v68, v0
	v_mov_b32_e32 v69, v0
	v_mov_b32_e32 v70, v0
	v_mov_b32_e32 v71, v0
	v_mov_b32_e32 v8, v0
	v_mov_b32_e32 v9, v0
	v_mov_b32_e32 v10, v0
	v_mov_b32_e32 v11, v0
	v_mov_b32_e32 v12, v0
	v_mov_b32_e32 v13, v0
	v_mov_b32_e32 v14, v0
	v_mov_b32_e32 v15, v0
	v_mov_b32_e32 v24, v0
	v_mov_b32_e32 v25, v0
	v_mov_b32_e32 v26, v0
	v_mov_b32_e32 v27, v0
	v_mov_b32_e32 v28, v0
	v_mov_b32_e32 v29, v0
	v_mov_b32_e32 v30, v0
	v_mov_b32_e32 v31, v0
	v_mov_b32_e32 v56, v0
	v_mov_b32_e32 v57, v0
	v_mov_b32_e32 v58, v0
	v_mov_b32_e32 v59, v0
	v_mov_b32_e32 v60, v0
	v_mov_b32_e32 v61, v0
	v_mov_b32_e32 v62, v0
	v_mov_b32_e32 v63, v0
	v_mov_b32_e32 v72, v0
	v_mov_b32_e32 v73, v0
	v_mov_b32_e32 v74, v0
	v_mov_b32_e32 v75, v0
	v_mov_b32_e32 v76, v0
	v_mov_b32_e32 v77, v0
	v_mov_b32_e32 v78, v0
	v_mov_b32_e32 v79, v0
	v_mov_b32_e32 v80, v0
	v_mov_b32_e32 v81, v0
	v_mov_b32_e32 v82, v0
	v_mov_b32_e32 v83, v0
	v_mov_b32_e32 v84, v0
	v_mov_b32_e32 v85, v0
	v_mov_b32_e32 v86, v0
	v_mov_b32_e32 v87, v0
	v_mov_b32_e32 v96, v0
	v_mov_b32_e32 v97, v0
	v_mov_b32_e32 v98, v0
	v_mov_b32_e32 v99, v0
	v_mov_b32_e32 v100, v0
	v_mov_b32_e32 v101, v0
	v_mov_b32_e32 v102, v0
	v_mov_b32_e32 v103, v0
	v_mov_b32_e32 v112, v0
	v_mov_b32_e32 v113, v0
	v_mov_b32_e32 v114, v0
	v_mov_b32_e32 v115, v0
	v_mov_b32_e32 v116, v0
	v_mov_b32_e32 v117, v0
	v_mov_b32_e32 v118, v0
	v_mov_b32_e32 v119, v0
	v_mov_b32_e32 v132, v0
	v_mov_b32_e32 v133, v0
	v_mov_b32_e32 v134, v0
	v_mov_b32_e32 v135, v0
	v_mov_b32_e32 v136, v0
	v_mov_b32_e32 v137, v0
	v_mov_b32_e32 v138, v0
	v_mov_b32_e32 v139, v0
	v_mov_b32_e32 v88, v0
	v_mov_b32_e32 v89, v0
	v_mov_b32_e32 v90, v0
	v_mov_b32_e32 v91, v0
	v_mov_b32_e32 v92, v0
	v_mov_b32_e32 v93, v0
	v_mov_b32_e32 v94, v0
	v_mov_b32_e32 v95, v0
	v_mov_b32_e32 v104, v0
	v_mov_b32_e32 v105, v0
	v_mov_b32_e32 v106, v0
	v_mov_b32_e32 v107, v0
	v_mov_b32_e32 v108, v0
	v_mov_b32_e32 v109, v0
	v_mov_b32_e32 v110, v0
	v_mov_b32_e32 v111, v0
	v_mov_b32_e32 v120, v0
	v_mov_b32_e32 v121, v0
	v_mov_b32_e32 v122, v0
	v_mov_b32_e32 v123, v0
	v_mov_b32_e32 v124, v0
	v_mov_b32_e32 v125, v0
	v_mov_b32_e32 v126, v0
	v_mov_b32_e32 v127, v0
	v_mov_b32_e32 v140, v0
	v_mov_b32_e32 v141, v0
	v_mov_b32_e32 v142, v0
	v_mov_b32_e32 v143, v0
	v_mov_b32_e32 v144, v0
	v_mov_b32_e32 v145, v0
	v_mov_b32_e32 v146, v0
	v_mov_b32_e32 v147, v0
	.p2align	6

; template <class Epi, class Sched, bool ALIGN_EPI = false, bool SP2 = false>
; __device__ __forceinline__ void gemm_phase(PG8_LAS unsigned char* lds, const Gemm g, const Sched& S, const Epi& E) {
;     ...
;         const bool has_next = S.next(ui + 1, nxt);
;         const char* nA = has_next ? (const char*)g.A + (size_t)nxt.pm * tstep : cA; const char* nB = has_next ? (const char*)g.Bt + (size_t)nxt.pn * tstep : cB;
;     ...
; #pragma unroll
;         for (int a = 0; a < 2; ++a)
; #pragma unroll
;             for (int b = 0; b < 2; ++b)
; #pragma unroll
;                 for (int m = 0; m < 4; ++m)
; #pragma unroll
;                     for (int n = 0; n < 2; ++n) acc[a][b][m][n] = (f32x4){0.f, 0.f, 0.f, 0.f};
.LBB0_1697:
	s_ashr_i32 s55, s54, 31
	s_lshl_b64 s[6:7], s[54:55], 19
	s_add_u32 s56, s36, s6
	s_addc_u32 s57, s37, s7
	s_and_b64 s[6:7], s[48:49], exec
	s_cselect_b32 s29, s57, s61
	s_cselect_b32 s55, s56, s60
	s_ashr_i32 s53, s52, 31
	s_lshl_b64 s[6:7], s[52:53], 19
	s_add_u32 s58, s5, s6
	s_addc_u32 s59, s27, s7
	s_and_b64 s[6:7], s[48:49], exec
	s_cselect_b32 s53, s59, s79
	s_cselect_b32 s68, s58, s78
	s_add_u32 s60, s60, 0x40080
	s_addc_u32 s61, s61, 0
	s_add_u32 s69, s78, 0x100
	v_mov_b32_e32 v0, 0
	s_addc_u32 s33, s79, 0
	s_mov_b32 s72, -2
	s_waitcnt lgkmcnt(0)
	v_mov_b32_e32 v1, v0
	v_mov_b32_e32 v2, v0
	v_mov_b32_e32 v3, v0
	v_mov_b32_e32 v4, v0
	v_mov_b32_e32 v5, v0
	v_mov_b32_e32 v6, v0
	v_mov_b32_e32 v7, v0
	v_mov_b32_e32 v16, v0
	v_mov_b32_e32 v17, v0
	v_mov_b32_e32 v18, v0
	v_mov_b32_e32 v19, v0
	v_mov_b32_e32 v20, v0
	v_mov_b32_e32 v21, v0
	v_mov_b32_e32 v22, v0
	v_mov_b32_e32 v23, v0
	v_mov_b32_e32 v32, v0
	v_mov_b32_e32 v33, v0
	v_mov_b32_e32 v34, v0
	v_mov_b32_e32 v35, v0
	s_waitcnt vmcnt(0)
	v_mov_b32_e32 v36, v0
	v_mov_b32_e32 v37, v0
	v_mov_b32_e32 v38, v0
	v_mov_b32_e32 v39, v0
	v_mov_b32_e32 v48, v0
	v_mov_b32_e32 v49, v0
	v_mov_b32_e32 v50, v0
	v_mov_b32_e32 v51, v0
	v_mov_b32_e32 v52, v0
	v_mov_b32_e32 v53, v0
	v_mov_b32_e32 v54, v0
	v_mov_b32_e32 v55, v0
	v_mov_b32_e32 v8, v0
	v_mov_b32_e32 v9, v0
	v_mov_b32_e32 v10, v0
	v_mov_b32_e32 v11, v0
	v_mov_b32_e32 v12, v0
	v_mov_b32_e32 v13, v0
	v_mov_b32_e32 v14, v0
	v_mov_b32_e32 v15, v0
	v_mov_b32_e32 v24, v0
	v_mov_b32_e32 v25, v0
	v_mov_b32_e32 v26, v0
	v_mov_b32_e32 v27, v0
	v_mov_b32_e32 v28, v0
	v_mov_b32_e32 v29, v0
	v_mov_b32_e32 v30, v0
	v_mov_b32_e32 v31, v0
	v_mov_b32_e32 v40, v0
	v_mov_b32_e32 v41, v0
	v_mov_b32_e32 v42, v0
	v_mov_b32_e32 v43, v0
	v_mov_b32_e32 v44, v0
	v_mov_b32_e32 v45, v0
	v_mov_b32_e32 v46, v0
	v_mov_b32_e32 v47, v0
	v_mov_b32_e32 v56, v0
	v_mov_b32_e32 v57, v0
	v_mov_b32_e32 v58, v0
	v_mov_b32_e32 v59, v0
	v_mov_b32_e32 v60, v0
	v_mov_b32_e32 v61, v0
	v_mov_b32_e32 v62, v0
	v_mov_b32_e32 v63, v0
	v_mov_b32_e32 v64, v0
	v_mov_b32_e32 v65, v0
	v_mov_b32_e32 v66, v0
	v_mov_b32_e32 v67, v0
	v_mov_b32_e32 v68, v0
	v_mov_b32_e32 v69, v0
	v_mov_b32_e32 v70, v0
	v_mov_b32_e32 v71, v0
	v_mov_b32_e32 v80, v0
	v_mov_b32_e32 v81, v0
	v_mov_b32_e32 v82, v0
	v_mov_b32_e32 v83, v0
	v_mov_b32_e32 v84, v0
	v_mov_b32_e32 v85, v0
	v_mov_b32_e32 v86, v0
	v_mov_b32_e32 v87, v0
	v_mov_b32_e32 v96, v0
	v_mov_b32_e32 v97, v0
	v_mov_b32_e32 v98, v0
	v_mov_b32_e32 v99, v0
	v_mov_b32_e32 v100, v0
	v_mov_b32_e32 v101, v0
	v_mov_b32_e32 v102, v0
	v_mov_b32_e32 v103, v0
	v_mov_b32_e32 v112, v0
	v_mov_b32_e32 v113, v0
	v_mov_b32_e32 v114, v0
	v_mov_b32_e32 v115, v0
	v_mov_b32_e32 v116, v0
	v_mov_b32_e32 v117, v0
	v_mov_b32_e32 v118, v0
	v_mov_b32_e32 v119, v0
	v_mov_b32_e32 v72, v0
	v_mov_b32_e32 v73, v0
	v_mov_b32_e32 v74, v0
	v_mov_b32_e32 v75, v0
	v_mov_b32_e32 v76, v0
	v_mov_b32_e32 v77, v0
	v_mov_b32_e32 v78, v0
	v_mov_b32_e32 v79, v0
	v_mov_b32_e32 v88, v0
	v_mov_b32_e32 v89, v0
	v_mov_b32_e32 v90, v0
	v_mov_b32_e32 v91, v0
	v_mov_b32_e32 v92, v0
	v_mov_b32_e32 v93, v0
	v_mov_b32_e32 v94, v0
	v_mov_b32_e32 v95, v0
	v_mov_b32_e32 v104, v0
	v_mov_b32_e32 v105, v0
	v_mov_b32_e32 v106, v0
	v_mov_b32_e32 v107, v0
	v_mov_b32_e32 v108, v0
	v_mov_b32_e32 v109, v0
	v_mov_b32_e32 v110, v0
	v_mov_b32_e32 v111, v0
	v_mov_b32_e32 v120, v0
	v_mov_b32_e32 v121, v0
	v_mov_b32_e32 v122, v0
	v_mov_b32_e32 v123, v0
	v_mov_b32_e32 v124, v0
	v_mov_b32_e32 v125, v0
	v_mov_b32_e32 v126, v0
	v_mov_b32_e32 v127, v0
	.p2align	6

; template <class Epi, class Sched, bool ALIGN_EPI = false, bool SP2 = false>
; __device__ __forceinline__ void gemm_phase(PG8_LAS unsigned char* lds, const Gemm g, const Sched& S, const Epi& E) {
;     ...
;         const bool has_next = S.next(ui + 1, nxt);
;         const char* nA = has_next ? (const char*)g.A + (size_t)nxt.pm * tstep : cA; const char* nB = has_next ? (const char*)g.Bt + (size_t)nxt.pn * tstep : cB;
;     ...
; #pragma unroll
;         for (int a = 0; a < 2; ++a)
; #pragma unroll
;             for (int b = 0; b < 2; ++b)
; #pragma unroll
;                 for (int m = 0; m < 4; ++m)
; #pragma unroll
;                     for (int n = 0; n < 2; ++n) acc[a][b][m][n] = (f32x4){0.f, 0.f, 0.f, 0.f};
.LBB0_1821:
	s_ashr_i32 s39, s38, 31
	s_lshl_b64 s[6:7], s[38:39], 19
	s_add_u32 s40, s22, s6
	s_addc_u32 s41, s23, s7
	s_and_b64 s[6:7], s[44:45], exec
	s_cselect_b32 s39, s41, s51
	s_cselect_b32 s69, s40, s50
	s_ashr_i32 s37, s36, 31
	s_lshl_b64 s[6:7], s[36:37], 19
	s_add_u32 s46, s4, s6
	s_addc_u32 s47, s5, s7
	s_and_b64 s[6:7], s[44:45], exec
	s_cselect_b32 s37, s47, s53
	s_cselect_b32 s74, s46, s52
	s_add_u32 s50, s50, 0x40080
	s_addc_u32 s51, s51, 0
	s_add_u32 s75, s52, 0x100
	v_mov_b32_e32 v0, 0
	s_addc_u32 s33, s53, 0
	s_mov_b32 s72, -2
	v_mov_b32_e32 v1, v0
	v_mov_b32_e32 v2, v0
	v_mov_b32_e32 v3, v0
	v_mov_b32_e32 v8, v0
	v_mov_b32_e32 v9, v0
	v_mov_b32_e32 v10, v0
	v_mov_b32_e32 v11, v0
	v_mov_b32_e32 v16, v0
	v_mov_b32_e32 v17, v0
	v_mov_b32_e32 v18, v0
	v_mov_b32_e32 v19, v0
	v_mov_b32_e32 v24, v0
	v_mov_b32_e32 v25, v0
	v_mov_b32_e32 v26, v0
	v_mov_b32_e32 v27, v0
	v_mov_b32_e32 v32, v0
	v_mov_b32_e32 v33, v0
	v_mov_b32_e32 v34, v0
	v_mov_b32_e32 v35, v0
	v_mov_b32_e32 v40, v0
	v_mov_b32_e32 v41, v0
	v_mov_b32_e32 v42, v0
	v_mov_b32_e32 v43, v0
	v_mov_b32_e32 v48, v0
	v_mov_b32_e32 v49, v0
	v_mov_b32_e32 v50, v0
	v_mov_b32_e32 v51, v0
	v_mov_b32_e32 v56, v0
	v_mov_b32_e32 v57, v0
	v_mov_b32_e32 v58, v0
	v_mov_b32_e32 v59, v0
	v_mov_b32_e32 v4, v0
	v_mov_b32_e32 v5, v0
	v_mov_b32_e32 v6, v0
	v_mov_b32_e32 v7, v0
	v_mov_b32_e32 v12, v0
	v_mov_b32_e32 v13, v0
	v_mov_b32_e32 v14, v0
	v_mov_b32_e32 v15, v0
	v_mov_b32_e32 v20, v0
	v_mov_b32_e32 v21, v0
	v_mov_b32_e32 v22, v0
	v_mov_b32_e32 v23, v0
	v_mov_b32_e32 v28, v0
	v_mov_b32_e32 v29, v0
	v_mov_b32_e32 v30, v0
	v_mov_b32_e32 v31, v0
	v_mov_b32_e32 v36, v0
	v_mov_b32_e32 v37, v0
	v_mov_b32_e32 v38, v0
	v_mov_b32_e32 v39, v0
	v_mov_b32_e32 v44, v0
	v_mov_b32_e32 v45, v0
	v_mov_b32_e32 v46, v0
	v_mov_b32_e32 v47, v0
	v_mov_b32_e32 v52, v0
	v_mov_b32_e32 v53, v0
	v_mov_b32_e32 v54, v0
	v_mov_b32_e32 v55, v0
	v_mov_b32_e32 v60, v0
	v_mov_b32_e32 v61, v0
	v_mov_b32_e32 v62, v0
	v_mov_b32_e32 v63, v0
	v_mov_b32_e32 v64, v0
	v_mov_b32_e32 v65, v0
	v_mov_b32_e32 v66, v0
	v_mov_b32_e32 v67, v0
	v_mov_b32_e32 v72, v0
	v_mov_b32_e32 v73, v0
	v_mov_b32_e32 v74, v0
	v_mov_b32_e32 v75, v0
	v_mov_b32_e32 v80, v0
	v_mov_b32_e32 v81, v0
	v_mov_b32_e32 v82, v0
	v_mov_b32_e32 v83, v0
	v_mov_b32_e32 v88, v0
	v_mov_b32_e32 v89, v0
	v_mov_b32_e32 v90, v0
	v_mov_b32_e32 v91, v0
	v_mov_b32_e32 v96, v0
	v_mov_b32_e32 v97, v0
	v_mov_b32_e32 v98, v0
	v_mov_b32_e32 v99, v0
	v_mov_b32_e32 v104, v0
	v_mov_b32_e32 v105, v0
	v_mov_b32_e32 v106, v0
	v_mov_b32_e32 v107, v0
	v_mov_b32_e32 v112, v0
	v_mov_b32_e32 v113, v0
	v_mov_b32_e32 v114, v0
	v_mov_b32_e32 v115, v0
	v_mov_b32_e32 v120, v0
	v_mov_b32_e32 v121, v0
	v_mov_b32_e32 v122, v0
	v_mov_b32_e32 v123, v0
	v_mov_b32_e32 v68, v0
	v_mov_b32_e32 v69, v0
	v_mov_b32_e32 v70, v0
	v_mov_b32_e32 v71, v0
	v_mov_b32_e32 v76, v0
	v_mov_b32_e32 v77, v0
	v_mov_b32_e32 v78, v0
	v_mov_b32_e32 v79, v0
	v_mov_b32_e32 v84, v0
	v_mov_b32_e32 v85, v0
	v_mov_b32_e32 v86, v0
	v_mov_b32_e32 v87, v0
	v_mov_b32_e32 v92, v0
	v_mov_b32_e32 v93, v0
	v_mov_b32_e32 v94, v0
	v_mov_b32_e32 v95, v0
	v_mov_b32_e32 v100, v0
	v_mov_b32_e32 v101, v0
	v_mov_b32_e32 v102, v0
	v_mov_b32_e32 v103, v0
	v_mov_b32_e32 v108, v0
	v_mov_b32_e32 v109, v0
	v_mov_b32_e32 v110, v0
	v_mov_b32_e32 v111, v0
	v_mov_b32_e32 v116, v0
	v_mov_b32_e32 v117, v0
	v_mov_b32_e32 v118, v0
	v_mov_b32_e32 v119, v0
	v_mov_b32_e32 v124, v0
	v_mov_b32_e32 v125, v0
	v_mov_b32_e32 v126, v0
	v_mov_b32_e32 v127, v0
	.p2align	6

; template <class Epi, class Sched, bool ALIGN_EPI = false, bool SP2 = false>
; __device__ __forceinline__ void gemm_phase(PG8_LAS unsigned char* lds, const Gemm g, const Sched& S, const Epi& E) {
;     ...
;         for (int t = 0; t < nt; t += 2) {
;             const bool last = (t == nt - 2);
;             const char* a1 = cA + (size_t)(t + 1) * kstep;
;             const char* a2 = last ? nA : cA + (size_t)(t + 2) * kstep; const char* b2 = last ? nB : cB + (size_t)(t + 2) * kstep;
;             const char* a3 = a2 + kstep; const char* b3 = b2 + kstep;
;     ...
; #pragma unroll
;         for (int a = 0; a < 2; ++a)
; #pragma unroll
;             for (int b = 0; b < 2; ++b)
; #pragma unroll
;                 for (int m = 0; m < 4; ++m)
; #pragma unroll
;                     for (int n = 0; n < 2; ++n) acc[a][b][m][n] = (f32x4){0.f, 0.f, 0.f, 0.f};
;         cur = nxt; cA = nA; cB = nB; ++ui;
.LBB0_1934:
	s_add_u32 s33, s50, 0x100
	v_mov_b32_e32 v0, 0
	s_addc_u32 s77, s51, 0
	s_mov_b32 s72, -2
	s_waitcnt lgkmcnt(0)
	v_mov_b32_e32 v1, v0
	v_mov_b32_e32 v2, v0
	v_mov_b32_e32 v3, v0
	v_mov_b32_e32 v4, v0
	v_mov_b32_e32 v5, v0
	v_mov_b32_e32 v6, v0
	v_mov_b32_e32 v7, v0
	v_mov_b32_e32 v16, v0
	v_mov_b32_e32 v17, v0
	v_mov_b32_e32 v18, v0
	v_mov_b32_e32 v19, v0
	v_mov_b32_e32 v20, v0
	v_mov_b32_e32 v21, v0
	v_mov_b32_e32 v22, v0
	v_mov_b32_e32 v23, v0
	v_mov_b32_e32 v32, v0
	v_mov_b32_e32 v33, v0
	v_mov_b32_e32 v34, v0
	v_mov_b32_e32 v35, v0
	v_mov_b32_e32 v36, v0
	v_mov_b32_e32 v37, v0
	v_mov_b32_e32 v38, v0
	v_mov_b32_e32 v39, v0
	v_mov_b32_e32 v48, v0
	v_mov_b32_e32 v49, v0
	v_mov_b32_e32 v50, v0
	v_mov_b32_e32 v51, v0
	v_mov_b32_e32 v52, v0
	v_mov_b32_e32 v53, v0
	v_mov_b32_e32 v54, v0
	v_mov_b32_e32 v55, v0
	v_mov_b32_e32 v8, v0
	v_mov_b32_e32 v9, v0
	v_mov_b32_e32 v10, v0
	v_mov_b32_e32 v11, v0
	v_mov_b32_e32 v12, v0
	v_mov_b32_e32 v13, v0
	v_mov_b32_e32 v14, v0
	v_mov_b32_e32 v15, v0
	v_mov_b32_e32 v24, v0
	v_mov_b32_e32 v25, v0
	v_mov_b32_e32 v26, v0
	v_mov_b32_e32 v27, v0
	v_mov_b32_e32 v28, v0
	v_mov_b32_e32 v29, v0
	v_mov_b32_e32 v30, v0
	v_mov_b32_e32 v31, v0
	v_mov_b32_e32 v40, v0
	v_mov_b32_e32 v41, v0
	v_mov_b32_e32 v42, v0
	v_mov_b32_e32 v43, v0
	v_mov_b32_e32 v44, v0
	v_mov_b32_e32 v45, v0
	v_mov_b32_e32 v46, v0
	v_mov_b32_e32 v47, v0
	v_mov_b32_e32 v56, v0
	v_mov_b32_e32 v57, v0
	v_mov_b32_e32 v58, v0
	v_mov_b32_e32 v59, v0
	v_mov_b32_e32 v60, v0
	v_mov_b32_e32 v61, v0
	v_mov_b32_e32 v62, v0
	v_mov_b32_e32 v63, v0
	v_mov_b32_e32 v64, v0
	v_mov_b32_e32 v65, v0
	v_mov_b32_e32 v66, v0
	v_mov_b32_e32 v67, v0
	v_mov_b32_e32 v68, v0
	v_mov_b32_e32 v69, v0
	v_mov_b32_e32 v70, v0
	v_mov_b32_e32 v71, v0
	v_mov_b32_e32 v80, v0
	v_mov_b32_e32 v81, v0
	v_mov_b32_e32 v82, v0
	v_mov_b32_e32 v83, v0
	v_mov_b32_e32 v84, v0
	v_mov_b32_e32 v85, v0
	v_mov_b32_e32 v86, v0
	v_mov_b32_e32 v87, v0
	v_mov_b32_e32 v96, v0
	v_mov_b32_e32 v97, v0
	v_mov_b32_e32 v98, v0
	v_mov_b32_e32 v99, v0
	v_mov_b32_e32 v100, v0
	v_mov_b32_e32 v101, v0
	v_mov_b32_e32 v102, v0
	v_mov_b32_e32 v103, v0
	v_mov_b32_e32 v112, v0
	v_mov_b32_e32 v113, v0
	v_mov_b32_e32 v114, v0
	v_mov_b32_e32 v115, v0
	v_mov_b32_e32 v116, v0
	v_mov_b32_e32 v117, v0
	v_mov_b32_e32 v118, v0
	v_mov_b32_e32 v119, v0
	v_mov_b32_e32 v72, v0
	v_mov_b32_e32 v73, v0
	v_mov_b32_e32 v74, v0
	v_mov_b32_e32 v75, v0
	v_mov_b32_e32 v76, v0
	v_mov_b32_e32 v77, v0
	v_mov_b32_e32 v78, v0
	v_mov_b32_e32 v79, v0
	v_mov_b32_e32 v88, v0
	v_mov_b32_e32 v89, v0
	v_mov_b32_e32 v90, v0
	v_mov_b32_e32 v91, v0
	v_mov_b32_e32 v92, v0
	v_mov_b32_e32 v93, v0
	v_mov_b32_e32 v94, v0
	v_mov_b32_e32 v95, v0
	v_mov_b32_e32 v104, v0
	v_mov_b32_e32 v105, v0
	v_mov_b32_e32 v106, v0
	v_mov_b32_e32 v107, v0
	v_mov_b32_e32 v108, v0
	v_mov_b32_e32 v109, v0
	v_mov_b32_e32 v110, v0
	v_mov_b32_e32 v111, v0
	v_mov_b32_e32 v120, v0
	v_mov_b32_e32 v121, v0
	v_mov_b32_e32 v122, v0
	v_mov_b32_e32 v123, v0
	v_mov_b32_e32 v124, v0
	v_mov_b32_e32 v125, v0
	v_mov_b32_e32 v126, v0
	v_mov_b32_e32 v127, v0
	.p2align	6
